# epilogue policy refined: nt kept only on full-line streams (P3 f32 x loads, final output stores), removed from bf16 half-line base loads in P7/P9
# speedup vs baseline: 1.0110x; 1.0110x over previous
; __device__ __forceinline__ unsigned cvt_pk_bf16(float lo, float hi) { f32x2_cv v = {lo, hi}; bf16x2_cv b = __builtin_convertvector(v, bf16x2_cv); return __builtin_bit_cast(unsigned, b); }
;     __device__ __forceinline__ void operator()(const f32x4 (&acc)[2][2][4][2], const Unit& u, int wr, int wc, int fr, int fq) const {
;         const float* g = gate + (u.pm >> 5) * 9216;
;         const int row0 = u.pm * BM + wr * 64 + fr, col0 = u.pn * BM + wc * 32 + 8 * fq;
;         f32x4 gv[2][2];
; #pragma unroll
;         for (int bj = 0; bj < 2; ++bj)
; #pragma unroll
;             for (int n = 0; n < 2; ++n) gv[bj][n] = *(const f32x4*)(g + col0 + bj * HALF + 4 * n) * coef;
; #pragma unroll
;         for (int ai = 0; ai < 2; ++ai)
; #pragma unroll
;             for (int m = 0; m < 4; ++m) {
;                 const int row = row0 + ai * HALF + m * 16; const size_t off = (size_t)row * 1024 + col0;
;                 f32x4 b0[2], b1[2];
; #pragma unroll
;                 for (int bj = 0; bj < 2; ++bj) {
;                     if (BASE_BF16) { const u32x4 t = *(const u32x4*)((const bf16_t*)base + off + bj * HALF);
;                         b0[bj] = (f32x4){bf_lo(t.x), bf_hi(t.x), bf_lo(t.y), bf_hi(t.y)}; b1[bj] = (f32x4){bf_lo(t.z), bf_hi(t.z), bf_lo(t.w), bf_hi(t.w)}; }
;                     else { b0[bj] = *(const f32x4*)((const float*)base + off + bj * HALF); b1[bj] = *(const f32x4*)((const float*)base + off + bj * HALF + 4); }
;                 }
;                 float ss = 0.f;
; #pragma unroll
;                 for (int bj = 0; bj < 2; ++bj) {
;                     const f32x4 v0 = b0[bj] + gv[bj][0] * acc[ai][bj][m][0], v1 = b1[bj] + gv[bj][1] * acc[ai][bj][m][1];
;                     if (OUT_BF16) {
;                         u32x4 w; w.x = cvt_pk_bf16(v0[0], v0[1]); w.y = cvt_pk_bf16(v0[2], v0[3]); w.z = cvt_pk_bf16(v1[0], v1[1]); w.w = cvt_pk_bf16(v1[2], v1[3]);
;                         *(u32x4*)((bf16_t*)out + off + bj * HALF) = w;
;                         ss += ((v0[0] * v0[0] + v0[1] * v0[1]) + (v0[2] * v0[2] + v0[3] * v0[3])) + ((v1[0] * v1[0] + v1[1] * v1[1]) + (v1[2] * v1[2] + v1[3] * v1[3]));
;                     } else { *(f32x4*)((float*)out + off + bj * HALF) = v0; *(f32x4*)((float*)out + off + bj * HALF + 4) = v1; }
.LBB0_1010:
	s_lshr_b32 s22, s49, 5
	s_mulk_i32 s22, 0x2400
	v_lshl_add_u32 v164, s49, 8, v166
	s_ashr_i32 s23, s22, 31
	v_lshl_or_b32 v162, s50, 8, v168
	v_ashrrev_i32_e32 v165, 31, v164
	s_lshl_b64 s[22:23], s[22:23], 2
	v_ashrrev_i32_e32 v163, 31, v162
	v_lshlrev_b64 v[144:145], 10, v[164:165]
	s_add_u32 s22, s39, s22
	v_lshl_add_u64 v[160:161], v[144:145], 0, v[162:163]
	s_addc_u32 s23, s40, s23
	v_lshl_add_u64 v[148:149], v[160:161], 1, s[24:25]
	v_lshl_add_u64 v[176:177], v[162:163], 2, s[22:23]
	global_load_dwordx4 v[144:147], v[148:149], off
	s_nop 0
	global_load_dwordx4 v[148:151], v[148:149], off offset:256
	s_nop 0
	global_load_dwordx4 v[152:155], v[176:177], off
	global_load_dwordx4 v[156:159], v[176:177], off offset:16
	global_load_dwordx4 v[172:175], v[176:177], off offset:512
	s_nop 0
	global_load_dwordx4 v[176:179], v[176:177], off offset:528
	v_or_b32_e32 v180, 16, v164
	v_ashrrev_i32_e32 v181, 31, v180
	v_lshlrev_b64 v[180:181], 10, v[180:181]
	v_lshl_add_u64 v[182:183], v[160:161], 2, s[84:85]
	v_lshl_add_u64 v[180:181], v[180:181], 0, v[162:163]
	v_lshl_add_u64 v[184:185], v[180:181], 1, s[24:25]
	s_and_b64 vcc, exec, s[0:1]
	s_mov_b64 s[0:1], -1
	s_waitcnt vmcnt(0)
	v_lshlrev_b32_e32 v186, 16, v144
	v_and_b32_e32 v187, 0xffff0000, v144
	v_lshlrev_b32_e32 v188, 16, v145
	v_and_b32_e32 v189, 0xffff0000, v145
	v_lshlrev_b32_e32 v190, 16, v146
	v_and_b32_e32 v191, 0xffff0000, v146
	v_lshlrev_b32_e32 v192, 16, v147
	v_and_b32_e32 v193, 0xffff0000, v147
	v_pk_mul_f32 v[144:145], v[154:155], 0.5 op_sel_hi:[1,0]
	v_pk_mul_f32 v[146:147], v[152:153], 0.5 op_sel_hi:[1,0]
	v_lshlrev_b32_e32 v194, 16, v148
	v_and_b32_e32 v195, 0xffff0000, v148
	v_lshlrev_b32_e32 v196, 16, v149
	v_and_b32_e32 v197, 0xffff0000, v149
	v_lshlrev_b32_e32 v198, 16, v150
	v_and_b32_e32 v199, 0xffff0000, v150
	v_lshlrev_b32_e32 v200, 16, v151
	v_and_b32_e32 v201, 0xffff0000, v151
	v_pk_mul_f32 v[148:149], v[158:159], 0.5 op_sel_hi:[1,0]
	v_pk_mul_f32 v[150:151], v[156:157], 0.5 op_sel_hi:[1,0]
	v_pk_mul_f32 v[152:153], v[174:175], 0.5 op_sel_hi:[1,0]
	v_pk_mul_f32 v[154:155], v[172:173], 0.5 op_sel_hi:[1,0]
	v_pk_mul_f32 v[156:157], v[178:179], 0.5 op_sel_hi:[1,0]
	v_pk_mul_f32 v[158:159], v[176:177], 0.5 op_sel_hi:[1,0]
	v_pk_fma_f32 v[124:125], v[124:125], v[146:147], v[186:187]
	v_pk_fma_f32 v[126:127], v[126:127], v[144:145], v[188:189]
	v_pk_fma_f32 v[120:121], v[120:121], v[150:151], v[190:191]
	v_pk_fma_f32 v[122:123], v[122:123], v[148:149], v[192:193]
	v_pk_fma_f32 v[116:117], v[116:117], v[154:155], v[194:195]
	v_pk_fma_f32 v[118:119], v[118:119], v[152:153], v[196:197]
	v_pk_fma_f32 v[112:113], v[112:113], v[158:159], v[198:199]
	v_pk_fma_f32 v[114:115], v[114:115], v[156:157], v[200:201]
	global_store_dwordx4 v[182:183], v[124:127], off nt
	global_store_dwordx4 v[182:183], v[120:123], off offset:16 nt
	global_store_dwordx4 v[182:183], v[116:119], off offset:512 nt
	global_store_dwordx4 v[182:183], v[112:115], off offset:528 nt
	global_load_dwordx4 v[112:115], v[184:185], off
	s_nop 0
	global_load_dwordx4 v[116:119], v[184:185], off offset:256
	v_or_b32_e32 v120, 32, v164
	v_ashrrev_i32_e32 v121, 31, v120
	v_lshlrev_b64 v[120:121], 10, v[120:121]
	v_lshl_add_u64 v[120:121], v[120:121], 0, v[162:163]
	v_lshl_add_u64 v[122:123], v[180:181], 2, s[84:85]
	v_lshl_add_u64 v[124:125], v[120:121], 1, s[24:25]
	s_waitcnt vmcnt(1)
	v_lshlrev_b32_e32 v126, 16, v112
	v_and_b32_e32 v127, 0xffff0000, v112
	v_lshlrev_b32_e32 v112, 16, v113
	v_and_b32_e32 v113, 0xffff0000, v113
	v_lshlrev_b32_e32 v172, 16, v114
	v_and_b32_e32 v173, 0xffff0000, v114
	v_lshlrev_b32_e32 v114, 16, v115
	v_and_b32_e32 v115, 0xffff0000, v115
	s_waitcnt vmcnt(0)
	v_lshlrev_b32_e32 v174, 16, v116
	v_and_b32_e32 v175, 0xffff0000, v116
	v_lshlrev_b32_e32 v116, 16, v117
	v_and_b32_e32 v117, 0xffff0000, v117
	v_lshlrev_b32_e32 v176, 16, v118
	v_and_b32_e32 v177, 0xffff0000, v118
	v_lshlrev_b32_e32 v118, 16, v119
	v_and_b32_e32 v119, 0xffff0000, v119
	v_pk_fma_f32 v[110:111], v[110:111], v[144:145], v[112:113]
	v_pk_fma_f32 v[108:109], v[108:109], v[146:147], v[126:127]
	v_pk_fma_f32 v[106:107], v[106:107], v[148:149], v[114:115]
	v_pk_fma_f32 v[104:105], v[104:105], v[150:151], v[172:173]
	v_pk_fma_f32 v[102:103], v[102:103], v[152:153], v[116:117]
	v_pk_fma_f32 v[100:101], v[100:101], v[154:155], v[174:175]
	v_pk_fma_f32 v[98:99], v[98:99], v[156:157], v[118:119]
	v_pk_fma_f32 v[96:97], v[96:97], v[158:159], v[176:177]
	global_store_dwordx4 v[122:123], v[108:111], off nt
	global_store_dwordx4 v[122:123], v[104:107], off offset:16 nt
	global_store_dwordx4 v[122:123], v[100:103], off offset:512 nt
	global_store_dwordx4 v[122:123], v[96:99], off offset:528 nt
	global_load_dwordx4 v[96:99], v[124:125], off
	s_nop 0
	global_load_dwordx4 v[100:103], v[124:125], off offset:256
	v_or_b32_e32 v104, 48, v164
	v_ashrrev_i32_e32 v105, 31, v104
	v_lshlrev_b64 v[104:105], 10, v[104:105]
	v_lshl_add_u64 v[104:105], v[104:105], 0, v[162:163]
	v_lshl_add_u64 v[106:107], v[120:121], 2, s[84:85]
	v_lshl_add_u64 v[108:109], v[104:105], 1, s[24:25]
	s_waitcnt vmcnt(1)
	v_lshlrev_b32_e32 v110, 16, v96
	v_and_b32_e32 v111, 0xffff0000, v96
	v_lshlrev_b32_e32 v96, 16, v97
	v_and_b32_e32 v97, 0xffff0000, v97
	v_lshlrev_b32_e32 v112, 16, v98
	v_and_b32_e32 v113, 0xffff0000, v98
	v_lshlrev_b32_e32 v98, 16, v99
	v_and_b32_e32 v99, 0xffff0000, v99
	s_waitcnt vmcnt(0)
; __device__ __forceinline__ unsigned cvt_pk_bf16(float lo, float hi) { f32x2_cv v = {lo, hi}; bf16x2_cv b = __builtin_convertvector(v, bf16x2_cv); return __builtin_bit_cast(unsigned, b); }
;     __device__ __forceinline__ void operator()(const f32x4 (&acc)[2][2][4][2], const Unit& u, int wr, int wc, int fr, int fq) const {
;     ...
;         for (int ai = 0; ai < 2; ++ai)
; #pragma unroll
;             for (int m = 0; m < 4; ++m) {
;                 const int row = row0 + ai * HALF + m * 16; const size_t off = (size_t)row * 1024 + col0;
;                 f32x4 b0[2], b1[2];
; #pragma unroll
;                 for (int bj = 0; bj < 2; ++bj) {
;                     if (BASE_BF16) { const u32x4 t = *(const u32x4*)((const bf16_t*)base + off + bj * HALF);
;                         b0[bj] = (f32x4){bf_lo(t.x), bf_hi(t.x), bf_lo(t.y), bf_hi(t.y)}; b1[bj] = (f32x4){bf_lo(t.z), bf_hi(t.z), bf_lo(t.w), bf_hi(t.w)}; }
;                     else { b0[bj] = *(const f32x4*)((const float*)base + off + bj * HALF); b1[bj] = *(const f32x4*)((const float*)base + off + bj * HALF + 4); }
;                 }
;                 float ss = 0.f;
; #pragma unroll
;                 for (int bj = 0; bj < 2; ++bj) {
;                     const f32x4 v0 = b0[bj] + gv[bj][0] * acc[ai][bj][m][0], v1 = b1[bj] + gv[bj][1] * acc[ai][bj][m][1];
;                     if (OUT_BF16) {
;                         u32x4 w; w.x = cvt_pk_bf16(v0[0], v0[1]); w.y = cvt_pk_bf16(v0[2], v0[3]); w.z = cvt_pk_bf16(v1[0], v1[1]); w.w = cvt_pk_bf16(v1[2], v1[3]);
;                         *(u32x4*)((bf16_t*)out + off + bj * HALF) = w;
;                         ss += ((v0[0] * v0[0] + v0[1] * v0[1]) + (v0[2] * v0[2] + v0[3] * v0[3])) + ((v1[0] * v1[0] + v1[1] * v1[1]) + (v1[2] * v1[2] + v1[3] * v1[3]));
;                     } else { *(f32x4*)((float*)out + off + bj * HALF) = v0; *(f32x4*)((float*)out + off + bj * HALF + 4) = v1; }
	v_lshlrev_b32_e32 v114, 16, v100
	v_and_b32_e32 v115, 0xffff0000, v100
	v_lshlrev_b32_e32 v100, 16, v101
	v_and_b32_e32 v101, 0xffff0000, v101
	v_lshlrev_b32_e32 v116, 16, v102
	v_and_b32_e32 v117, 0xffff0000, v102
	v_lshlrev_b32_e32 v102, 16, v103
	v_and_b32_e32 v103, 0xffff0000, v103
	v_pk_fma_f32 v[94:95], v[94:95], v[144:145], v[96:97]
	v_pk_fma_f32 v[92:93], v[92:93], v[146:147], v[110:111]
	v_pk_fma_f32 v[90:91], v[90:91], v[148:149], v[98:99]
	v_pk_fma_f32 v[88:89], v[88:89], v[150:151], v[112:113]
	v_pk_fma_f32 v[86:87], v[86:87], v[152:153], v[100:101]
	v_pk_fma_f32 v[84:85], v[84:85], v[154:155], v[114:115]
	v_pk_fma_f32 v[82:83], v[82:83], v[156:157], v[102:103]
	v_pk_fma_f32 v[80:81], v[80:81], v[158:159], v[116:117]
	global_store_dwordx4 v[106:107], v[92:95], off nt
	global_store_dwordx4 v[106:107], v[88:91], off offset:16 nt
	global_store_dwordx4 v[106:107], v[84:87], off offset:512 nt
	global_store_dwordx4 v[106:107], v[80:83], off offset:528 nt
	global_load_dwordx4 v[80:83], v[108:109], off
	s_nop 0
	global_load_dwordx4 v[84:87], v[108:109], off offset:256
	v_lshl_add_u64 v[88:89], v[160:161], 0, s[12:13]
	v_lshl_add_u64 v[90:91], v[104:105], 2, s[84:85]
	v_lshl_add_u64 v[92:93], v[88:89], 1, s[24:25]
	s_waitcnt vmcnt(1)
	v_lshlrev_b32_e32 v94, 16, v80
	v_and_b32_e32 v95, 0xffff0000, v80
	v_lshlrev_b32_e32 v80, 16, v81
	v_and_b32_e32 v81, 0xffff0000, v81
	v_lshlrev_b32_e32 v96, 16, v82
	v_and_b32_e32 v97, 0xffff0000, v82
	v_lshlrev_b32_e32 v82, 16, v83
	v_and_b32_e32 v83, 0xffff0000, v83
	s_waitcnt vmcnt(0)
	v_lshlrev_b32_e32 v98, 16, v84
	v_and_b32_e32 v99, 0xffff0000, v84
	v_lshlrev_b32_e32 v84, 16, v85
	v_and_b32_e32 v85, 0xffff0000, v85
	v_lshlrev_b32_e32 v100, 16, v86
	v_and_b32_e32 v101, 0xffff0000, v86
	v_lshlrev_b32_e32 v86, 16, v87
	v_and_b32_e32 v87, 0xffff0000, v87
	v_pk_fma_f32 v[78:79], v[78:79], v[144:145], v[80:81]
	v_pk_fma_f32 v[76:77], v[76:77], v[146:147], v[94:95]
	v_pk_fma_f32 v[74:75], v[74:75], v[148:149], v[82:83]
	v_pk_fma_f32 v[72:73], v[72:73], v[150:151], v[96:97]
	v_pk_fma_f32 v[70:71], v[70:71], v[152:153], v[84:85]
	v_pk_fma_f32 v[68:69], v[68:69], v[154:155], v[98:99]
	v_pk_fma_f32 v[66:67], v[66:67], v[156:157], v[86:87]
	v_pk_fma_f32 v[64:65], v[64:65], v[158:159], v[100:101]
	global_store_dwordx4 v[90:91], v[76:79], off nt
	global_store_dwordx4 v[90:91], v[72:75], off offset:16 nt
	global_store_dwordx4 v[90:91], v[68:71], off offset:512 nt
	global_store_dwordx4 v[90:91], v[64:67], off offset:528 nt
	global_load_dwordx4 v[64:67], v[92:93], off
	s_nop 0
	global_load_dwordx4 v[68:71], v[92:93], off offset:256
	v_lshl_add_u64 v[72:73], v[160:161], 0, s[14:15]
	v_lshl_add_u64 v[74:75], v[88:89], 2, s[84:85]
	v_lshl_add_u64 v[76:77], v[72:73], 1, s[24:25]
	s_waitcnt vmcnt(1)
	v_lshlrev_b32_e32 v78, 16, v64
	v_and_b32_e32 v79, 0xffff0000, v64
	v_lshlrev_b32_e32 v64, 16, v65
	v_and_b32_e32 v65, 0xffff0000, v65
	v_lshlrev_b32_e32 v80, 16, v66
	v_and_b32_e32 v81, 0xffff0000, v66
	v_lshlrev_b32_e32 v66, 16, v67
	v_and_b32_e32 v67, 0xffff0000, v67
	s_waitcnt vmcnt(0)
	v_lshlrev_b32_e32 v82, 16, v68
	v_and_b32_e32 v83, 0xffff0000, v68
	v_lshlrev_b32_e32 v68, 16, v69
	v_and_b32_e32 v69, 0xffff0000, v69
	v_lshlrev_b32_e32 v84, 16, v70
	v_and_b32_e32 v85, 0xffff0000, v70
	v_lshlrev_b32_e32 v70, 16, v71
	v_and_b32_e32 v71, 0xffff0000, v71
	v_pk_fma_f32 v[62:63], v[62:63], v[144:145], v[64:65]
	v_pk_fma_f32 v[60:61], v[60:61], v[146:147], v[78:79]
	v_pk_fma_f32 v[58:59], v[58:59], v[148:149], v[66:67]
	v_pk_fma_f32 v[56:57], v[56:57], v[150:151], v[80:81]
	v_pk_fma_f32 v[54:55], v[54:55], v[152:153], v[68:69]
	v_pk_fma_f32 v[52:53], v[52:53], v[154:155], v[82:83]
	v_pk_fma_f32 v[50:51], v[50:51], v[156:157], v[70:71]
	v_pk_fma_f32 v[48:49], v[48:49], v[158:159], v[84:85]
	global_store_dwordx4 v[74:75], v[60:63], off nt
	global_store_dwordx4 v[74:75], v[56:59], off offset:16 nt
	global_store_dwordx4 v[74:75], v[52:55], off offset:512 nt
	global_store_dwordx4 v[74:75], v[48:51], off offset:528 nt
	global_load_dwordx4 v[48:51], v[76:77], off
	s_nop 0
	global_load_dwordx4 v[52:55], v[76:77], off offset:256
	v_lshl_add_u64 v[56:57], v[160:161], 0, s[16:17]
	v_lshl_add_u64 v[58:59], v[72:73], 2, s[84:85]
	v_lshl_add_u64 v[60:61], v[56:57], 1, s[24:25]
	s_waitcnt vmcnt(1)
; template <class Epi, class Sched, bool ALIGN_EPI = false, bool SP2 = false>
; __device__ __forceinline__ void gemm_phase(PG8_LAS unsigned char* lds, const Gemm g, const Sched& S, const Epi& E) {
;     ...
;         if (!has_next) break;
;         if constexpr (!Epi::CHAIN) {
; #pragma unroll
;         for (int a = 0; a < 2; ++a)
; #pragma unroll
;             for (int b = 0; b < 2; ++b)
; #pragma unroll
;                 for (int m = 0; m < 4; ++m)
; #pragma unroll
;                     for (int n = 0; n < 2; ++n) acc[a][b][m][n] = (f32x4){0.f, 0.f, 0.f, 0.f};
;         }
;         cur = nxt; cA = nA; cB = nB; ++ui;
;         if constexpr (ALIGN_EPI) { if (wr == 1) PG8_BAR; }
;     __device__ __forceinline__ void operator()(const f32x4 (&acc)[2][2][4][2], const Unit& u, int wr, int wc, int fr, int fq) const {
;     ...
;         for (int ai = 0; ai < 2; ++ai)
; #pragma unroll
;             for (int m = 0; m < 4; ++m) {
;                 const int row = row0 + ai * HALF + m * 16; const size_t off = (size_t)row * 1024 + col0;
;                 f32x4 b0[2], b1[2];
; #pragma unroll
;                 for (int bj = 0; bj < 2; ++bj) {
;                     if (BASE_BF16) { const u32x4 t = *(const u32x4*)((const bf16_t*)base + off + bj * HALF);
;                         b0[bj] = (f32x4){bf_lo(t.x), bf_hi(t.x), bf_lo(t.y), bf_hi(t.y)}; b1[bj] = (f32x4){bf_lo(t.z), bf_hi(t.z), bf_lo(t.w), bf_hi(t.w)}; }
;                     else { b0[bj] = *(const f32x4*)((const float*)base + off + bj * HALF); b1[bj] = *(const f32x4*)((const float*)base + off + bj * HALF + 4); }
;                 }
;                 float ss = 0.f;
; #pragma unroll
;                 for (int bj = 0; bj < 2; ++bj) {
;                     const f32x4 v0 = b0[bj] + gv[bj][0] * acc[ai][bj][m][0], v1 = b1[bj] + gv[bj][1] * acc[ai][bj][m][1];
;                     if (OUT_BF16) {
;                         u32x4 w; w.x = cvt_pk_bf16(v0[0], v0[1]); w.y = cvt_pk_bf16(v0[2], v0[3]); w.z = cvt_pk_bf16(v1[0], v1[1]); w.w = cvt_pk_bf16(v1[2], v1[3]);
;                         *(u32x4*)((bf16_t*)out + off + bj * HALF) = w;
;                         ss += ((v0[0] * v0[0] + v0[1] * v0[1]) + (v0[2] * v0[2] + v0[3] * v0[3])) + ((v1[0] * v1[0] + v1[1] * v1[1]) + (v1[2] * v1[2] + v1[3] * v1[3]));
;                     } else { *(f32x4*)((float*)out + off + bj * HALF) = v0; *(f32x4*)((float*)out + off + bj * HALF + 4) = v1; }
	v_lshlrev_b32_e32 v62, 16, v48
	v_and_b32_e32 v63, 0xffff0000, v48
	v_lshlrev_b32_e32 v48, 16, v49
	v_and_b32_e32 v49, 0xffff0000, v49
	v_lshlrev_b32_e32 v64, 16, v50
	v_and_b32_e32 v65, 0xffff0000, v50
	v_lshlrev_b32_e32 v50, 16, v51
	v_and_b32_e32 v51, 0xffff0000, v51
	s_waitcnt vmcnt(0)
	v_lshlrev_b32_e32 v66, 16, v52
	v_and_b32_e32 v67, 0xffff0000, v52
	v_lshlrev_b32_e32 v52, 16, v53
	v_and_b32_e32 v53, 0xffff0000, v53
	v_lshlrev_b32_e32 v68, 16, v54
	v_and_b32_e32 v69, 0xffff0000, v54
	v_lshlrev_b32_e32 v54, 16, v55
	v_and_b32_e32 v55, 0xffff0000, v55
	v_pk_fma_f32 v[46:47], v[46:47], v[144:145], v[48:49]
	v_pk_fma_f32 v[44:45], v[44:45], v[146:147], v[62:63]
	v_pk_fma_f32 v[42:43], v[42:43], v[148:149], v[50:51]
	v_pk_fma_f32 v[40:41], v[40:41], v[150:151], v[64:65]
	v_pk_fma_f32 v[38:39], v[38:39], v[152:153], v[52:53]
	v_pk_fma_f32 v[36:37], v[36:37], v[154:155], v[66:67]
	v_pk_fma_f32 v[34:35], v[34:35], v[156:157], v[54:55]
	v_pk_fma_f32 v[32:33], v[32:33], v[158:159], v[68:69]
	global_store_dwordx4 v[58:59], v[44:47], off nt
	global_store_dwordx4 v[58:59], v[40:43], off offset:16 nt
	global_store_dwordx4 v[58:59], v[36:39], off offset:512 nt
	global_store_dwordx4 v[58:59], v[32:35], off offset:528 nt
	global_load_dwordx4 v[32:35], v[60:61], off
	s_nop 0
	global_load_dwordx4 v[36:39], v[60:61], off offset:256
	v_lshl_add_u64 v[40:41], v[160:161], 0, s[18:19]
	v_lshl_add_u64 v[42:43], v[56:57], 2, s[84:85]
	v_lshl_add_u64 v[44:45], v[40:41], 1, s[24:25]
	s_waitcnt vmcnt(1)
	v_lshlrev_b32_e32 v46, 16, v32
	v_and_b32_e32 v47, 0xffff0000, v32
	v_lshlrev_b32_e32 v32, 16, v33
	v_and_b32_e32 v33, 0xffff0000, v33
	v_lshlrev_b32_e32 v48, 16, v34
	v_and_b32_e32 v49, 0xffff0000, v34
	v_lshlrev_b32_e32 v34, 16, v35
	v_and_b32_e32 v35, 0xffff0000, v35
	s_waitcnt vmcnt(0)
	v_lshlrev_b32_e32 v50, 16, v36
	v_and_b32_e32 v51, 0xffff0000, v36
	v_lshlrev_b32_e32 v36, 16, v37
	v_and_b32_e32 v37, 0xffff0000, v37
	v_lshlrev_b32_e32 v52, 16, v38
	v_and_b32_e32 v53, 0xffff0000, v38
	v_lshlrev_b32_e32 v38, 16, v39
	v_and_b32_e32 v39, 0xffff0000, v39
	v_pk_fma_f32 v[30:31], v[30:31], v[144:145], v[32:33]
	v_pk_fma_f32 v[28:29], v[28:29], v[146:147], v[46:47]
	v_pk_fma_f32 v[26:27], v[26:27], v[148:149], v[34:35]
	v_pk_fma_f32 v[24:25], v[24:25], v[150:151], v[48:49]
	v_pk_fma_f32 v[22:23], v[22:23], v[152:153], v[36:37]
	v_pk_fma_f32 v[20:21], v[20:21], v[154:155], v[50:51]
	v_pk_fma_f32 v[18:19], v[18:19], v[156:157], v[38:39]
	v_pk_fma_f32 v[16:17], v[16:17], v[158:159], v[52:53]
	global_store_dwordx4 v[42:43], v[28:31], off nt
	global_store_dwordx4 v[42:43], v[24:27], off offset:16 nt
	global_store_dwordx4 v[42:43], v[20:23], off offset:512 nt
	global_store_dwordx4 v[42:43], v[16:19], off offset:528 nt
	global_load_dwordx4 v[16:19], v[44:45], off
	s_nop 0
	global_load_dwordx4 v[20:23], v[44:45], off offset:256
	v_lshl_add_u64 v[24:25], v[40:41], 2, s[84:85]
	s_waitcnt vmcnt(1)
	v_lshlrev_b32_e32 v26, 16, v16
	v_and_b32_e32 v27, 0xffff0000, v16
	v_lshlrev_b32_e32 v16, 16, v17
	v_and_b32_e32 v17, 0xffff0000, v17
	v_lshlrev_b32_e32 v28, 16, v18
	v_and_b32_e32 v29, 0xffff0000, v18
	v_lshlrev_b32_e32 v18, 16, v19
	v_and_b32_e32 v19, 0xffff0000, v19
	s_waitcnt vmcnt(0)
	v_lshlrev_b32_e32 v30, 16, v20
	v_and_b32_e32 v31, 0xffff0000, v20
	v_lshlrev_b32_e32 v20, 16, v21
	v_and_b32_e32 v21, 0xffff0000, v21
	v_lshlrev_b32_e32 v32, 16, v22
	v_and_b32_e32 v33, 0xffff0000, v22
	v_lshlrev_b32_e32 v22, 16, v23
	v_and_b32_e32 v23, 0xffff0000, v23
	v_pk_fma_f32 v[14:15], v[14:15], v[144:145], v[16:17]
	v_pk_fma_f32 v[12:13], v[12:13], v[146:147], v[26:27]
	v_pk_fma_f32 v[10:11], v[10:11], v[148:149], v[18:19]
	v_pk_fma_f32 v[8:9], v[8:9], v[150:151], v[28:29]
	v_pk_fma_f32 v[6:7], v[6:7], v[152:153], v[20:21]
	v_pk_fma_f32 v[4:5], v[4:5], v[154:155], v[30:31]
	v_pk_fma_f32 v[2:3], v[2:3], v[156:157], v[22:23]
	v_pk_fma_f32 v[0:1], v[0:1], v[158:159], v[32:33]
	global_store_dwordx4 v[24:25], v[12:15], off nt
	global_store_dwordx4 v[24:25], v[8:11], off offset:16 nt
	global_store_dwordx4 v[24:25], v[4:7], off offset:512 nt
	global_store_dwordx4 v[24:25], v[0:3], off offset:528 nt
	s_cbranch_vccnz .LBB0_995
	s_andn2_b64 vcc, exec, s[6:7]
	s_cbranch_vccnz .LBB0_994
	s_barrier
	s_branch .LBB0_994
